# attention: S accumulator -m initialisation moves packed with v_pk_mov_b32
# baseline (speedup 1.0000x reference)
.LBB0_452:
	v_mov_b32_e32 v14, v0
	v_mov_b32_e32 v15, v0
	v_mov_b32_e32 v1, v0
	v_pk_mov_b32 v[2:3], v[0:1], v[0:1] op_sel:[0,0]
	v_pk_mov_b32 v[4:5], v[0:1], v[0:1] op_sel:[0,0]
	v_pk_mov_b32 v[6:7], v[0:1], v[0:1] op_sel:[0,0]
	v_pk_mov_b32 v[8:9], v[0:1], v[0:1] op_sel:[0,0]
	v_pk_mov_b32 v[10:11], v[0:1], v[0:1] op_sel:[0,0]
	v_pk_mov_b32 v[12:13], v[0:1], v[0:1] op_sel:[0,0]
	v_mov_b64_e32 v[30:31], v[14:15]
	v_mov_b64_e32 v[62:63], v[14:15]
	v_mov_b64_e32 v[46:47], v[14:15]
	v_mov_b64_e32 v[78:79], v[14:15]
	v_mov_b32_e32 v241, 0
	v_mov_b32_e32 v197, v195
	v_mov_b32_e32 v239, v195
	v_mov_b32_e32 v238, 0
	v_mov_b64_e32 v[28:29], v[12:13]
	v_mov_b64_e32 v[26:27], v[10:11]
	v_mov_b64_e32 v[24:25], v[8:9]
	v_mov_b64_e32 v[22:23], v[6:7]
	v_mov_b64_e32 v[20:21], v[4:5]
	v_mov_b64_e32 v[18:19], v[2:3]
	v_mov_b64_e32 v[16:17], v[0:1]
	v_mov_b64_e32 v[60:61], v[12:13]
	v_mov_b64_e32 v[58:59], v[10:11]
	v_mov_b64_e32 v[56:57], v[8:9]
	v_mov_b64_e32 v[54:55], v[6:7]
	v_mov_b64_e32 v[52:53], v[4:5]
	v_mov_b64_e32 v[50:51], v[2:3]
	v_mov_b64_e32 v[48:49], v[0:1]
	v_mov_b64_e32 v[44:45], v[12:13]
	v_mov_b64_e32 v[42:43], v[10:11]
	v_mov_b64_e32 v[40:41], v[8:9]
	v_mov_b64_e32 v[38:39], v[6:7]
	v_mov_b64_e32 v[36:37], v[4:5]
	v_mov_b64_e32 v[34:35], v[2:3]
	v_mov_b64_e32 v[32:33], v[0:1]
	v_mov_b64_e32 v[76:77], v[12:13]
	v_mov_b64_e32 v[74:75], v[10:11]
	v_mov_b64_e32 v[72:73], v[8:9]
	v_mov_b64_e32 v[70:71], v[6:7]
	v_mov_b64_e32 v[68:69], v[4:5]
	v_mov_b64_e32 v[66:67], v[2:3]
	v_mov_b64_e32 v[64:65], v[0:1]

.LBB0_493:
	s_cmp_lt_i32 s14, s34
	s_cselect_b64 s[4:5], -1, 0
	s_and_b64 s[4:5], s[10:11], s[4:5]
	s_add_i32 s15, s12, 64
	s_cmp_lt_u32 s12, 0xfffffeff
	s_cselect_b64 s[12:13], -1, 0
	s_and_b64 s[12:13], s[4:5], s[12:13]
	s_and_b64 vcc, exec, s[12:13]
	s_cbranch_vccnz .LBB0_503
	s_cmp_lt_u32 s15, 0xffffff7f
	s_cselect_b64 s[12:13], -1, 0
	s_and_b64 s[12:13], s[4:5], s[12:13]
	ds_read_b128 v[10:13], v217
	ds_read_b128 v[244:247], v217 offset:32
	v_xor_b32_e32 v112, 0x80000000, v197
	v_xor_b32_e32 v80, 0x80000000, v239
	v_mov_b32_e32 v113, v112
	v_pk_mov_b32 v[114:115], v[112:113], v[112:113] op_sel:[0,0]
	v_pk_mov_b32 v[116:117], v[112:113], v[112:113] op_sel:[0,0]
	v_pk_mov_b32 v[118:119], v[112:113], v[112:113] op_sel:[0,0]
	v_pk_mov_b32 v[120:121], v[112:113], v[112:113] op_sel:[0,0]
	v_pk_mov_b32 v[122:123], v[112:113], v[112:113] op_sel:[0,0]
	v_pk_mov_b32 v[124:125], v[112:113], v[112:113] op_sel:[0,0]
	v_pk_mov_b32 v[126:127], v[112:113], v[112:113] op_sel:[0,0]
	v_mov_b32_e32 v81, v80
	v_pk_mov_b32 v[82:83], v[80:81], v[80:81] op_sel:[0,0]
	v_pk_mov_b32 v[84:85], v[80:81], v[80:81] op_sel:[0,0]
	v_pk_mov_b32 v[86:87], v[80:81], v[80:81] op_sel:[0,0]
	v_pk_mov_b32 v[88:89], v[80:81], v[80:81] op_sel:[0,0]
	v_pk_mov_b32 v[90:91], v[80:81], v[80:81] op_sel:[0,0]
	v_pk_mov_b32 v[92:93], v[80:81], v[80:81] op_sel:[0,0]
	v_pk_mov_b32 v[94:95], v[80:81], v[80:81] op_sel:[0,0]
	s_waitcnt lgkmcnt(1)
	v_mfma_f32_32x32x16_bf16 v[128:143], v[10:13], v[144:147], v[112:127]
	ds_read_b128 v[204:207], v218
	ds_read_b128 v[248:251], v217 offset:64
	ds_read_b128 v[230:233], v217 offset:96
	v_mfma_f32_32x32x16_bf16 v[96:111], v[10:13], v[160:163], v[80:95]
	ds_read_b128 v[10:13], v218 offset:32
	s_waitcnt lgkmcnt(4)
	v_mfma_f32_32x32x16_bf16 v[128:143], v[244:247], v[148:151], v[128:143]
	v_mfma_f32_32x32x16_bf16 v[96:111], v[244:247], v[164:167], v[96:111]
	s_waitcnt lgkmcnt(3)
	v_mfma_f32_32x32x16_bf16 v[112:127], v[204:207], v[144:147], v[112:127]
	v_mfma_f32_32x32x16_bf16 v[80:95], v[204:207], v[160:163], v[80:95]
	ds_read_b128 v[204:207], v218 offset:64
	s_waitcnt lgkmcnt(3)
	v_mfma_f32_32x32x16_bf16 v[128:143], v[248:251], v[152:155], v[128:143]
	v_mfma_f32_32x32x16_bf16 v[96:111], v[248:251], v[168:171], v[96:111]
	s_waitcnt lgkmcnt(1)
	v_mfma_f32_32x32x16_bf16 v[80:95], v[10:13], v[164:167], v[80:95]
	v_mfma_f32_32x32x16_bf16 v[112:127], v[10:13], v[148:151], v[112:127]
	v_mfma_f32_32x32x16_bf16 v[128:143], v[230:233], v[156:159], v[128:143]
	v_mfma_f32_32x32x16_bf16 v[96:111], v[230:233], v[172:175], v[96:111]
	ds_read_b128 v[230:233], v218 offset:96
	s_waitcnt lgkmcnt(1)
	v_mfma_f32_32x32x16_bf16 v[80:95], v[204:207], v[168:171], v[80:95]
	v_mfma_f32_32x32x16_bf16 v[112:127], v[204:207], v[152:155], v[112:127]
	s_waitcnt lgkmcnt(0)
	v_mfma_f32_32x32x16_bf16 v[80:95], v[230:233], v[172:175], v[80:95]
	v_mfma_f32_32x32x16_bf16 v[112:127], v[230:233], v[156:159], v[112:127]
	v_cndmask_b32_e64 v1, 0, 1, s[12:13]
	v_cmp_ne_u32_e64 s[4:5], 1, v1
	s_andn2_b64 vcc, exec, s[12:13]
	s_cbranch_vccnz .LBB0_496
	v_add_u32_e32 v1, v193, v240
	v_add_u32_e32 v12, 0xffffff7f, v1
	v_cmp_lt_u32_e32 vcc, s91, v12
	v_add_u32_e32 v13, 0xffffff5f, v1
	v_cmp_lt_u32_e64 s[20:21], s91, v13
	v_add_u32_e32 v14, 0xffffff7e, v1
	v_cmp_lt_u32_e64 s[40:41], s91, v14
	v_cndmask_b32_e32 v128, v234, v128, vcc
	v_add_u32_e32 v12, 0xffffff5e, v1
	v_cmp_lt_u32_e32 vcc, s91, v12
	v_cndmask_b32_e64 v112, v234, v112, s[20:21]
	v_add_u32_e32 v13, 0xffffff7d, v1
	v_cmp_lt_u32_e64 s[20:21], s91, v13
	v_cndmask_b32_e64 v129, v234, v129, s[40:41]
	v_add_u32_e32 v14, 0xffffff5d, v1
	v_cmp_lt_u32_e64 s[40:41], s91, v14
	v_cndmask_b32_e32 v113, v234, v113, vcc
	v_add_u32_e32 v12, 0xffffff7c, v1
	v_cmp_lt_u32_e32 vcc, s91, v12
	v_cndmask_b32_e64 v130, v234, v130, s[20:21]
	v_add_u32_e32 v13, 0xffffff5c, v1
	v_cmp_lt_u32_e64 s[20:21], s91, v13
	v_cndmask_b32_e64 v114, v234, v114, s[40:41]
	v_add_u32_e32 v14, 0xffffff77, v1
	v_cmp_lt_u32_e64 s[40:41], s91, v14
	v_cndmask_b32_e32 v131, v234, v131, vcc
	v_add_u32_e32 v12, 0xffffff57, v1
	v_cmp_lt_u32_e32 vcc, s91, v12
	v_cndmask_b32_e64 v115, v234, v115, s[20:21]
	v_add_u32_e32 v13, 0xffffff76, v1
	v_cmp_lt_u32_e64 s[20:21], s91, v13
	v_cndmask_b32_e64 v132, v234, v132, s[40:41]
	v_add_u32_e32 v14, 0xffffff56, v1
	v_cmp_lt_u32_e64 s[40:41], s91, v14
	v_cndmask_b32_e32 v116, v234, v116, vcc
	v_add_u32_e32 v12, 0xffffff75, v1
	v_cmp_lt_u32_e32 vcc, s91, v12
	v_cndmask_b32_e64 v133, v234, v133, s[20:21]
	v_add_u32_e32 v13, 0xffffff55, v1
	v_cmp_lt_u32_e64 s[20:21], s91, v13
	v_cndmask_b32_e64 v117, v234, v117, s[40:41]
	v_add_u32_e32 v14, 0xffffff74, v1
	v_cmp_lt_u32_e64 s[40:41], s91, v14
	v_cndmask_b32_e32 v134, v234, v134, vcc
	v_add_u32_e32 v12, 0xffffff54, v1
	v_cmp_lt_u32_e32 vcc, s91, v12
	v_cndmask_b32_e64 v118, v234, v118, s[20:21]
	v_add_u32_e32 v13, 0xffffff6f, v1
	v_cmp_lt_u32_e64 s[20:21], s91, v13
	v_cndmask_b32_e64 v135, v234, v135, s[40:41]
	v_add_u32_e32 v14, 0xffffff4f, v1
	v_cmp_lt_u32_e64 s[40:41], s91, v14
	v_cndmask_b32_e32 v119, v234, v119, vcc
	v_add_u32_e32 v12, 0xffffff6e, v1
	v_cmp_lt_u32_e32 vcc, s91, v12
	v_cndmask_b32_e64 v136, v234, v136, s[20:21]
	v_add_u32_e32 v13, 0xffffff4e, v1
	v_cmp_lt_u32_e64 s[20:21], s91, v13
	v_cndmask_b32_e64 v120, v234, v120, s[40:41]
	v_add_u32_e32 v14, 0xffffff6d, v1
	v_cmp_lt_u32_e64 s[40:41], s91, v14
	v_cndmask_b32_e32 v137, v234, v137, vcc
	v_add_u32_e32 v12, 0xffffff4d, v1
	v_cmp_lt_u32_e32 vcc, s91, v12
	v_cndmask_b32_e64 v121, v234, v121, s[20:21]
	v_add_u32_e32 v13, 0xffffff6c, v1
	v_cmp_lt_u32_e64 s[20:21], s91, v13
	v_cndmask_b32_e64 v138, v234, v138, s[40:41]
	v_add_u32_e32 v14, 0xffffff4c, v1
	v_cmp_lt_u32_e64 s[40:41], s91, v14
	v_cndmask_b32_e32 v122, v234, v122, vcc
	v_add_u32_e32 v12, 0xffffff67, v1
	v_cmp_lt_u32_e32 vcc, s91, v12
	v_cndmask_b32_e64 v139, v234, v139, s[20:21]
	v_add_u32_e32 v13, 0xffffff47, v1
	v_cmp_lt_u32_e64 s[20:21], s91, v13
	v_cndmask_b32_e64 v123, v234, v123, s[40:41]
	v_add_u32_e32 v14, 0xffffff66, v1
	v_cmp_lt_u32_e64 s[40:41], s91, v14
	v_cndmask_b32_e32 v140, v234, v140, vcc
	v_add_u32_e32 v12, 0xffffff46, v1
	v_cmp_lt_u32_e32 vcc, s91, v12
	v_cndmask_b32_e64 v124, v234, v124, s[20:21]
	v_add_u32_e32 v13, 0xffffff65, v1
	v_cmp_lt_u32_e64 s[20:21], s91, v13
	v_cndmask_b32_e64 v141, v234, v141, s[40:41]
	v_add_u32_e32 v14, 0xffffff45, v1
	v_cmp_lt_u32_e64 s[40:41], s91, v14
	v_cndmask_b32_e32 v125, v234, v125, vcc
	v_add_u32_e32 v12, 0xffffff64, v1
	v_cmp_lt_u32_e32 vcc, s91, v12
	v_cndmask_b32_e64 v142, v234, v142, s[20:21]
	v_add_u32_e32 v13, 0xffffff44, v1
	v_cmp_lt_u32_e64 s[20:21], s91, v13
	v_cndmask_b32_e64 v126, v234, v126, s[40:41]
	s_nop 0
	v_cndmask_b32_e32 v143, v234, v143, vcc
	v_cndmask_b32_e64 v127, v234, v127, s[20:21]
